# SWA attention unit prologue: bias-table loads issued together with the K/V DMAs and Q loads, LDS writes after the single drain (one memory round trip instead of three per unit); bit-exact
# speedup vs baseline: 1.0079x; 1.0007x over previous
.LBB0_1238:
	s_lshr_b32 s22, s33, 5
	s_and_b32 s22, s22, 3
	s_lshl_b32 s22, s22, 12
	s_lshl_b64 s[86:87], s[78:79], 20
	v_lshl_add_u64 v[4:5], v[156:157], 0, s[22:23]
	s_lshl_b32 s22, s51, 9
	s_add_u32 s36, s80, s22
	s_addc_u32 s37, s81, 0
	v_lshl_add_u64 v[6:7], s[36:37], 0, v[152:153]
	s_mov_b32 s36, m0
	s_mov_b32 m0, s21
	s_nop 0
	global_load_lds_dwordx4 v[6:7], off
	s_mov_b32 m0, s36
	s_add_u32 s36, s82, s22
	s_addc_u32 s37, s83, 0
	v_lshl_add_u64 v[6:7], s[36:37], 0, v[150:151]
	s_mov_b32 s36, m0
	s_mov_b32 m0, s26
	s_nop 0
	global_load_lds_dwordx4 v[6:7], off
	s_mov_b32 m0, s36
	s_add_u32 s36, s84, s22
	s_addc_u32 s37, s85, 0
	v_lshl_add_u64 v[6:7], s[36:37], 0, v[154:155]
	s_mov_b32 s36, m0
	s_mov_b32 m0, s27
	s_nop 0
	global_load_lds_dwordx4 v[6:7], off
	s_mov_b32 m0, s36
	s_bitset1_b32 s22, 15
	s_add_u32 s36, s80, s22
	s_addc_u32 s37, s81, 0
	v_lshl_add_u64 v[6:7], s[36:37], 0, v[152:153]
	s_mov_b32 s36, m0
	s_mov_b32 m0, s38
	s_nop 0
	global_load_lds_dwordx4 v[6:7], off
	s_mov_b32 m0, s36
	s_add_u32 s36, s82, s22
	s_addc_u32 s37, s83, 0
	v_lshl_add_u64 v[6:7], s[36:37], 0, v[150:151]
	s_mov_b32 s36, m0
	s_mov_b32 m0, s39
	s_nop 0
	global_load_lds_dwordx4 v[6:7], off
	s_mov_b32 m0, s36
	s_add_u32 s36, s84, s22
	s_addc_u32 s37, s85, 0
	v_lshl_add_u64 v[6:7], s[36:37], 0, v[154:155]
	s_mov_b32 s22, m0
	s_mov_b32 m0, s54
	s_nop 0
	global_load_lds_dwordx4 v[6:7], off
	s_mov_b32 m0, s22
	global_load_dword v252, v[4:5], off
	global_load_dword v253, v[4:5], off offset:2048
	s_lshl_b64 s[36:37], s[78:79], 24
	s_add_u32 s22, s58, s36
	s_addc_u32 s37, s59, s37
	s_lshl_b32 s66, s50, 10
	s_add_u32 s36, s22, s66
	s_addc_u32 s37, s37, 0
	s_lshl_b64 s[56:57], s[78:79], 25
	s_add_u32 s22, s48, s56
	s_addc_u32 s56, s49, s57
	s_add_u32 s80, s22, s66
	s_addc_u32 s81, s56, 0
	s_add_u32 s22, s70, s86
	s_addc_u32 s56, s71, s87
	s_lshl_b32 s50, s50, 5
	s_add_u32 s82, s22, s50
	s_addc_u32 s83, s56, 0
	s_add_u32 s56, s24, s50
	s_addc_u32 s57, s25, 0
	s_or_b32 s50, s51, s34
	v_or_b32_e32 v173, s50, v203
	v_lshlrev_b32_e32 v4, 12, v173
	v_mov_b32_e32 v5, v2
	v_lshl_add_u64 v[4:5], s[36:37], 0, v[4:5]
	v_mov_b32_e32 v161, v2
	v_lshl_add_u64 v[4:5], v[4:5], 0, v[160:161]
	s_mov_b32 s75, s23
	v_lshl_add_u64 v[6:7], v[4:5], 0, s[74:75]
	v_lshl_add_u64 v[4:5], s[30:31], 1, v[4:5]
	global_load_dwordx4 v[66:69], v[6:7], off
	global_load_dwordx4 v[70:73], v[6:7], off offset:32
	global_load_dwordx4 v[74:77], v[6:7], off offset:64
	global_load_dwordx4 v[78:81], v[6:7], off offset:96
	global_load_dwordx4 v[82:85], v[6:7], off offset:128
	global_load_dwordx4 v[86:89], v[6:7], off offset:160
	global_load_dwordx4 v[90:93], v[6:7], off offset:192
	global_load_dwordx4 v[94:97], v[6:7], off offset:224
	global_load_dwordx4 v[98:101], v[6:7], off offset:256
	global_load_dwordx4 v[102:105], v[6:7], off offset:288
	global_load_dwordx4 v[106:109], v[6:7], off offset:320
	global_load_dwordx4 v[110:113], v[6:7], off offset:352
	global_load_dwordx4 v[114:117], v[4:5], off offset:384
	global_load_dwordx4 v[118:121], v[4:5], off offset:416
	global_load_dwordx4 v[122:125], v[4:5], off offset:448
	global_load_dwordx4 v[126:129], v[4:5], off offset:480
	s_lshl_b32 s22, s55, 2
	v_mov_b32_e32 v3, s22
	v_mov_b32_e32 v4, s64
	global_load_dwordx3 v[146:148], v3, s[56:57]
	global_load_dword v161, v4, s[56:57]
	v_sub_co_u32_e32 v3, vcc, s50, v163
	s_nop 0
	v_readfirstlane_b32 s36, v3
	s_lshr_b32 s51, s36, 6
	v_mov_b32_e32 v5, v2
	v_lshlrev_b32_e32 v4, 13, v173
	s_and_b64 s[36:37], vcc, exec
	v_mov_b32_e32 v7, v2
	v_lshlrev_b32_e32 v6, 8, v173
	v_lshl_add_u64 v[4:5], s[80:81], 0, v[4:5]
	s_cselect_b32 s66, 0, s51
	s_lshr_b32 s67, s50, 6
	v_mov_b32_e32 v159, v2
	v_lshl_add_u64 v[6:7], s[82:83], 0, v[6:7]
	s_cmp_le_u32 s66, s67
	v_lshl_add_u64 v[4:5], v[4:5], 0, v[158:159]
	s_mov_b64 s[36:37], 0x1000
	s_mov_b32 s78, 0
	s_cselect_b64 s[80:81], -1, 0
	v_lshl_add_u64 v[166:167], v[6:7], 0, s[22:23]
	v_lshl_add_u64 v[168:169], v[4:5], 0, s[36:37]
	s_waitcnt vmcnt(17)
	s_waitcnt vmcnt(16)
	s_waitcnt vmcnt(15)
	s_waitcnt vmcnt(14)
	s_waitcnt vmcnt(13)
	s_waitcnt vmcnt(12)
	s_waitcnt vmcnt(11)
	s_waitcnt vmcnt(10)
	s_waitcnt vmcnt(9)
	s_waitcnt vmcnt(8)
	s_waitcnt vmcnt(7)
	s_waitcnt vmcnt(6)
	s_waitcnt vmcnt(5)
	s_waitcnt vmcnt(4)
	s_waitcnt vmcnt(3)
	s_waitcnt vmcnt(2)
	s_waitcnt vmcnt(0) lgkmcnt(0)
	ds_write_b32 v171, v252
	ds_write_b32 v171, v253 offset:2048
	s_waitcnt lgkmcnt(0)
	s_barrier
	s_waitcnt vmcnt(0)
	s_branch .LBB0_1242

	.amdhsa_kernel _Z10fwd_kernel4Args
		.amdhsa_group_segment_fixed_size 0
		.amdhsa_private_segment_fixed_size 0
		.amdhsa_kernarg_size 536
		.amdhsa_user_sgpr_count 2
		.amdhsa_user_sgpr_dispatch_ptr 0
		.amdhsa_user_sgpr_queue_ptr 0
		.amdhsa_user_sgpr_kernarg_segment_ptr 1
		.amdhsa_user_sgpr_dispatch_id 0
		.amdhsa_user_sgpr_kernarg_preload_length 0
		.amdhsa_user_sgpr_kernarg_preload_offset 0
		.amdhsa_user_sgpr_private_segment_size 0
		.amdhsa_uses_dynamic_stack 0
		.amdhsa_enable_private_segment 0
		.amdhsa_system_sgpr_workgroup_id_x 1
		.amdhsa_system_sgpr_workgroup_id_y 0
		.amdhsa_system_sgpr_workgroup_id_z 0
		.amdhsa_system_sgpr_workgroup_info 0
		.amdhsa_system_vgpr_workitem_id 0
		.amdhsa_next_free_vgpr 254
		.amdhsa_next_free_sgpr 102
		.amdhsa_accum_offset 256
		.amdhsa_reserve_vcc 1
		.amdhsa_float_round_mode_32 0
		.amdhsa_float_round_mode_16_64 0
		.amdhsa_float_denorm_mode_32 3
		.amdhsa_float_denorm_mode_16_64 3
		.amdhsa_dx10_clamp 1
		.amdhsa_ieee_mode 1
		.amdhsa_fp16_overflow 0
		.amdhsa_tg_split 0
		.amdhsa_exception_fp_ieee_invalid_op 0
		.amdhsa_exception_fp_denorm_src 0
		.amdhsa_exception_fp_ieee_div_zero 0
		.amdhsa_exception_fp_ieee_overflow 0
		.amdhsa_exception_fp_ieee_underflow 0
		.amdhsa_exception_fp_ieee_inexact 0
		.amdhsa_exception_int_div_zero 0
	.end_amdhsa_kernel

amdhsa.kernels:
  - .agpr_count:     0
    .args:
      - .offset:         0
        .size:           280
        .value_kind:     by_value
      - .offset:         280
        .size:           4
        .value_kind:     hidden_block_count_x
      - .offset:         284
        .size:           4
        .value_kind:     hidden_block_count_y
      - .offset:         288
        .size:           4
        .value_kind:     hidden_block_count_z
      - .offset:         292
        .size:           2
        .value_kind:     hidden_group_size_x
      - .offset:         294
        .size:           2
        .value_kind:     hidden_group_size_y
      - .offset:         296
        .size:           2
        .value_kind:     hidden_group_size_z
      - .offset:         298
        .size:           2
        .value_kind:     hidden_remainder_x
      - .offset:         300
        .size:           2
        .value_kind:     hidden_remainder_y
      - .offset:         302
        .size:           2
        .value_kind:     hidden_remainder_z
      - .offset:         320
        .size:           8
        .value_kind:     hidden_global_offset_x
      - .offset:         328
        .size:           8
        .value_kind:     hidden_global_offset_y
      - .offset:         336
        .size:           8
        .value_kind:     hidden_global_offset_z
      - .offset:         344
        .size:           2
        .value_kind:     hidden_grid_dims
      - .offset:         400
        .size:           4
        .value_kind:     hidden_dynamic_lds_size
    .group_segment_fixed_size: 0
    .kernarg_segment_align: 8
    .kernarg_segment_size: 536
    .language:       OpenCL C
    .language_version:
      - 2
      - 0
    .max_flat_workgroup_size: 512
    .name:           _Z10fwd_kernel4Args
    .private_segment_fixed_size: 0
    .sgpr_count:     108
    .sgpr_spill_count: 58
    .symbol:         _Z10fwd_kernel4Args.kd
    .uniform_work_group_size: 1
    .uses_dynamic_stack: false
    .vgpr_count:     254
    .vgpr_spill_count: 0
    .wavefront_size: 64
